# final RMSNorm phase: loop-invariant norm-weight loads hoisted out of the row loop
# baseline (speedup 1.0000x reference)
.LBB0_1215:
	s_lshl_b32 s2, s30, 3
	v_ashrrev_i32_e32 v2, 6, v173
	v_add_u32_e32 v8, s2, v2
	s_mov_b32 s0, 0x8000
	v_cmp_gt_i32_e32 vcc, s0, v8
	s_and_saveexec_b64 s[0:1], vcc
	s_cbranch_execz .LBB0_1218
	v_lshlrev_b32_e32 v0, 4, v173
	v_ashrrev_i32_e32 v3, 31, v2
	s_ashr_i32 s3, s2, 31
	v_and_b32_e32 v0, 0x3f0, v0
	v_mov_b32_e32 v1, 0
	v_lshl_add_u64 v[6:7], v[2:3], 0, s[2:3]
	v_lshl_add_u64 v[0:1], s[92:93], 0, v[0:1]
	s_mov_b64 s[0:1], 0x971a000
	v_lshlrev_b64 v[2:3], 6, v[6:7]
	v_lshlrev_b64 v[4:5], 11, v[6:7]
	v_and_b32_e32 v9, 63, v173
	v_lshlrev_b64 v[6:7], 12, v[6:7]
	v_readlane_b32 s8, v252, 0
	v_lshl_add_u64 v[0:1], v[0:1], 0, s[0:1]
	s_lshl_b32 s0, s94, 3
	v_lshl_or_b32 v6, v9, 4, v6
	v_readlane_b32 s14, v252, 6
	v_readlane_b32 s15, v252, 7
	s_ashr_i32 s1, s0, 31
	v_lshl_or_b32 v4, v9, 3, v4
	s_mov_b64 s[4:5], 0x19921400
	v_readlane_b32 s9, v252, 1
	v_readlane_b32 s10, v252, 2
	v_readlane_b32 s11, v252, 3
	v_readlane_b32 s12, v252, 4
	v_lshl_add_u64 v[6:7], s[14:15], 0, v[6:7]
	s_mov_b64 s[6:7], 0xc00
	s_lshl_b64 s[2:3], s[0:1], 6
	v_lshl_add_u64 v[4:5], v[4:5], 0, s[4:5]
	s_lshl_b64 s[4:5], s[0:1], 11
	v_lshl_add_u64 v[6:7], v[6:7], 0, s[6:7]
	s_lshl_b64 s[6:7], s[0:1], 12
	s_mov_b64 s[8:9], 0
	s_mov_b64 s[10:11], 0x9721000
	v_mov_b32_e32 v9, 0x358637bd
	s_mov_b32 s1, 0x800000
	s_movk_i32 s12, 0x7fff
	v_readlane_b32 s13, v252, 5
	global_load_dwordx4 v[64:67], v[0:1], off
	global_load_dwordx4 v[68:71], v[0:1], off offset:1024
	global_load_dwordx4 v[72:75], v[0:1], off offset:2048
	global_load_dwordx4 v[76:79], v[0:1], off offset:3072
.LBB0_1217:
	v_lshl_add_u64 v[22:23], s[92:93], 0, v[2:3]
	v_lshl_add_u64 v[42:43], s[92:93], 0, v[4:5]
	v_lshl_add_u64 v[44:45], v[22:23], 0, s[10:11]
	global_load_dwordx2 v[46:47], v[42:43], off offset:-1024
	v_add_co_u32_e32 v48, vcc, 0x9721000, v22
	global_load_dwordx2 v[50:51], v[42:43], off offset:-512
	global_load_dwordx2 v[52:53], v[42:43], off
	v_addc_co_u32_e32 v49, vcc, 0, v23, vcc
	global_load_dwordx4 v[22:25], v[44:45], off offset:32
	global_load_dwordx4 v[26:29], v[44:45], off offset:16
	global_load_dwordx4 v[30:33], v[48:49], off
	global_load_dwordx4 v[34:37], v[44:45], off offset:48
	global_load_dwordx2 v[54:55], v[42:43], off offset:512
	v_add_u32_e32 v8, s0, v8
	v_cmp_lt_i32_e32 vcc, s12, v8
	s_or_b64 s[8:9], vcc, s[8:9]
	s_waitcnt vmcnt(0)
	v_lshl_add_u64 v[2:3], v[2:3], 0, s[2:3]
	v_lshl_add_u64 v[4:5], v[4:5], 0, s[4:5]
	s_waitcnt vmcnt(8)
	v_lshlrev_b32_e32 v42, 16, v46
	v_and_b32_e32 v43, 0xffff0000, v46
	v_lshlrev_b32_e32 v44, 16, v47
	v_and_b32_e32 v45, 0xffff0000, v47
	s_waitcnt vmcnt(7)
	v_lshlrev_b32_e32 v46, 16, v50
	v_and_b32_e32 v47, 0xffff0000, v50
	v_lshlrev_b32_e32 v48, 16, v51
	v_and_b32_e32 v49, 0xffff0000, v51
	s_waitcnt vmcnt(6)
	v_lshlrev_b32_e32 v50, 16, v52
	v_and_b32_e32 v51, 0xffff0000, v52
	v_lshlrev_b32_e32 v52, 16, v53
	v_and_b32_e32 v53, 0xffff0000, v53
	s_waitcnt vmcnt(1)
	v_lshlrev_b32_e32 v56, 16, v54
	v_and_b32_e32 v57, 0xffff0000, v54
	v_mov_b32_e32 v58, v27
	v_mov_b32_e32 v59, v28
	v_mov_b32_e32 v27, v29
	v_pk_add_f32 v[28:29], v[42:43], 0 op_sel_hi:[1,0]
	v_pk_add_f32 v[42:43], v[44:45], 0 op_sel_hi:[1,0]
	v_pk_add_f32 v[44:45], v[46:47], 0 op_sel_hi:[1,0]
	v_pk_add_f32 v[46:47], v[48:49], 0 op_sel_hi:[1,0]
	v_pk_add_f32 v[48:49], v[50:51], 0 op_sel_hi:[1,0]
	v_pk_add_f32 v[50:51], v[52:53], 0 op_sel_hi:[1,0]
	v_pk_add_f32 v[52:53], v[56:57], 0 op_sel_hi:[1,0]
	v_mov_b32_e32 v56, v31
	v_mov_b32_e32 v57, v32
	v_mov_b32_e32 v31, v33
	v_add_f32_e32 v22, v22, v23
	v_add_f32_e32 v24, v24, v25
	v_pk_add_f32 v[26:27], v[58:59], v[26:27]
	v_mov_b32_e32 v23, v36
	v_mov_b32_e32 v25, v37
	v_pk_add_f32 v[30:31], v[56:57], v[30:31]
	v_pk_add_f32 v[26:27], v[26:27], v[26:27] op_sel:[0,1] op_sel_hi:[1,0]
	v_pk_add_f32 v[22:23], v[22:23], v[24:25]
	v_pk_add_f32 v[24:25], v[30:31], v[30:31] op_sel:[0,1] op_sel_hi:[1,0]
	v_mov_b32_e32 v27, v35
	v_mov_b32_e32 v25, v34
	v_pk_add_f32 v[24:25], v[24:25], v[26:27]
	v_lshlrev_b32_e32 v54, 16, v55
	v_pk_add_f32 v[22:23], v[24:25], v[22:23]
	v_and_b32_e32 v55, 0xffff0000, v55
	v_add_f32_e32 v22, v22, v23
	v_fmamk_f32 v22, v22, 0x3a800000, v9
	v_mul_f32_e32 v23, 0x4b800000, v22
	v_cmp_gt_f32_e32 vcc, s1, v22
	v_pk_add_f32 v[54:55], v[54:55], 0 op_sel_hi:[1,0]
	s_nop 0
	v_cndmask_b32_e32 v22, v22, v23, vcc
	v_rsq_f32_e32 v22, v22
	s_nop 0
	v_mul_f32_e32 v23, 0x45800000, v22
	v_cndmask_b32_e32 v22, v22, v23, vcc
	v_pk_mul_f32 v[24:25], v[28:29], v[22:23] op_sel_hi:[1,0]
	v_pk_mul_f32 v[26:27], v[42:43], v[22:23] op_sel_hi:[1,0]
	v_pk_mul_f32 v[28:29], v[44:45], v[22:23] op_sel_hi:[1,0]
	v_pk_mul_f32 v[30:31], v[46:47], v[22:23] op_sel_hi:[1,0]
	v_pk_mul_f32 v[32:33], v[48:49], v[22:23] op_sel_hi:[1,0]
	v_pk_mul_f32 v[34:35], v[50:51], v[22:23] op_sel_hi:[1,0]
	v_pk_mul_f32 v[36:37], v[52:53], v[22:23] op_sel_hi:[1,0]
	v_pk_mul_f32 v[42:43], v[54:55], v[22:23] op_sel_hi:[1,0]
	v_pk_mul_f32 v[10:11], v[64:65], v[24:25]
	v_pk_mul_f32 v[12:13], v[66:67], v[26:27]
	v_pk_mul_f32 v[14:15], v[68:69], v[28:29]
	v_pk_mul_f32 v[16:17], v[70:71], v[30:31]
	v_pk_mul_f32 v[18:19], v[72:73], v[32:33]
	v_pk_mul_f32 v[20:21], v[74:75], v[34:35]
	s_waitcnt vmcnt(0)
	v_pk_mul_f32 v[22:23], v[76:77], v[36:37]
	v_pk_mul_f32 v[24:25], v[78:79], v[42:43]
	global_store_dwordx4 v[6:7], v[10:13], off offset:-3072
	global_store_dwordx4 v[6:7], v[14:17], off offset:-2048
	global_store_dwordx4 v[6:7], v[18:21], off offset:-1024
	global_store_dwordx4 v[6:7], v[22:25], off
	v_lshl_add_u64 v[6:7], v[6:7], 0, s[6:7]
	s_andn2_b64 exec, exec, s[8:9]
	s_cbranch_execnz .LBB0_1217
